# dscan: hand-scheduled per-step compute on the computing wave for prompt tasks (ring-buffered LDS fragment reads, global stores)
# speedup vs baseline: 1.1588x; 1.0046x over previous
.LBB0_252:
	s_and_b64 vcc, exec, s[12:13]
	s_cbranch_vccz .Lds_orig
	s_mul_i32 s50, s64, 0xf400
	s_movk_i32 s51, 0x400
	v_and_b32_e32 v146, 15, v219
	v_lshrrev_b32_e32 v236, 4, v219
	v_lshlrev_b32_e32 v236, 3, v236
	v_mul_u32_u24_e32 v244, 0x110, v146
	v_mul_u32_u24_e32 v250, 0x90, v146
	v_add3_u32 v244, v244, v236, s50
	v_add3_u32 v250, v250, v236, s50
	v_mov_b32_e32 v146, v244
	ds_read2_b64 v[110:113], v146 offset0:0 offset1:4
	ds_read2_b64 v[114:117], v146 offset0:8 offset1:12
	ds_read2_b64 v[118:121], v146 offset0:16 offset1:20
	ds_read2_b64 v[122:125], v146 offset0:24 offset1:28
	v_add_u32_e32 v146, 0x1100, v244
	ds_read2_b64 v[168:171], v146 offset0:0 offset1:4
	ds_read2_b64 v[176:179], v146 offset0:8 offset1:12
	v_cvt_pk_bf16_f32 v94, v2, v3
	v_cvt_pk_bf16_f32 v95, v4, v5
	v_cvt_pk_bf16_f32 v96, v6, v7
	v_cvt_pk_bf16_f32 v97, v8, v9
	v_cvt_pk_bf16_f32 v98, v10, v11
	v_cvt_pk_bf16_f32 v99, v12, v13
	v_cvt_pk_bf16_f32 v100, v14, v15
	v_cvt_pk_bf16_f32 v101, v16, v17
	v_cvt_pk_bf16_f32 v102, v18, v19
	v_cvt_pk_bf16_f32 v103, v20, v21
	v_cvt_pk_bf16_f32 v104, v22, v23
	v_cvt_pk_bf16_f32 v105, v24, v25
	v_cvt_pk_bf16_f32 v106, v42, v43
	v_cvt_pk_bf16_f32 v107, v44, v45
	v_cvt_pk_bf16_f32 v108, v46, v47
	v_cvt_pk_bf16_f32 v109, v48, v49
	s_waitcnt lgkmcnt(5)
	v_mfma_f32_16x16x32_bf16 v[240:243], v[110:113], v[94:97], 0
	ds_read2_b64 v[110:113], v146 offset0:16 offset1:20
	s_waitcnt lgkmcnt(5)
	v_mfma_f32_16x16x32_bf16 v[240:243], v[114:117], v[98:101], v[240:243]
	ds_read2_b64 v[114:117], v146 offset0:24 offset1:28
	s_waitcnt lgkmcnt(5)
	v_mfma_f32_16x16x32_bf16 v[240:243], v[118:121], v[102:105], v[240:243]
	v_add_u32_e32 v146, 0x2200, v244
	ds_read2_b64 v[118:121], v146 offset0:0 offset1:4
	s_waitcnt lgkmcnt(5)
	v_mfma_f32_16x16x32_bf16 v[240:243], v[122:125], v[106:109], v[240:243]
	ds_read2_b64 v[122:125], v146 offset0:8 offset1:12
	s_waitcnt lgkmcnt(5)
	v_mfma_f32_16x16x32_bf16 v[246:249], v[168:171], v[94:97], 0
	ds_read2_b64 v[168:171], v146 offset0:16 offset1:20
	s_waitcnt lgkmcnt(5)
	v_mfma_f32_16x16x32_bf16 v[246:249], v[176:179], v[98:101], v[246:249]
	ds_read2_b64 v[176:179], v146 offset0:24 offset1:28
	s_waitcnt lgkmcnt(5)
	v_mfma_f32_16x16x32_bf16 v[246:249], v[110:113], v[102:105], v[246:249]
	v_add_u32_e32 v146, 0x3300, v244
	ds_read2_b64 v[110:113], v146 offset0:0 offset1:4
	s_waitcnt lgkmcnt(5)
	v_mfma_f32_16x16x32_bf16 v[246:249], v[114:117], v[106:109], v[246:249]
	ds_read2_b64 v[114:117], v146 offset0:8 offset1:12
	v_sub_f32_e32 v78, v78, v240
	v_sub_f32_e32 v79, v79, v241
	v_sub_f32_e32 v80, v80, v242
	v_sub_f32_e32 v81, v81, v243
	s_waitcnt lgkmcnt(5)
	v_mfma_f32_16x16x32_bf16 v[240:243], v[118:121], v[94:97], 0
	ds_read2_b64 v[118:121], v146 offset0:16 offset1:20
	s_waitcnt lgkmcnt(5)
	v_mfma_f32_16x16x32_bf16 v[240:243], v[122:125], v[98:101], v[240:243]
	ds_read2_b64 v[122:125], v146 offset0:24 offset1:28
	s_waitcnt lgkmcnt(5)
	v_mfma_f32_16x16x32_bf16 v[240:243], v[168:171], v[102:105], v[240:243]
	s_waitcnt lgkmcnt(4)
	v_mfma_f32_16x16x32_bf16 v[240:243], v[176:179], v[106:109], v[240:243]
	v_sub_f32_e32 v82, v82, v246
	v_sub_f32_e32 v83, v83, v247
	v_sub_f32_e32 v84, v84, v248
	v_sub_f32_e32 v85, v85, v249
	s_waitcnt lgkmcnt(3)
	v_mfma_f32_16x16x32_bf16 v[246:249], v[110:113], v[94:97], 0
	s_waitcnt lgkmcnt(2)
	v_mfma_f32_16x16x32_bf16 v[246:249], v[114:117], v[98:101], v[246:249]
	s_waitcnt lgkmcnt(1)
	v_mfma_f32_16x16x32_bf16 v[246:249], v[118:121], v[102:105], v[246:249]
	s_waitcnt lgkmcnt(0)
	v_mfma_f32_16x16x32_bf16 v[246:249], v[122:125], v[106:109], v[246:249]
	v_sub_f32_e32 v86, v86, v240
	v_sub_f32_e32 v87, v87, v241
	v_sub_f32_e32 v88, v88, v242
	v_sub_f32_e32 v89, v89, v243
	s_nop 7
	v_sub_f32_e32 v90, v90, v246
	v_sub_f32_e32 v91, v91, v247
	v_sub_f32_e32 v92, v92, v248
	v_sub_f32_e32 v93, v93, v249
	v_add_u32_e32 v146, 0x4400, v244
	ds_read2_b64 v[118:121], v146 offset0:0 offset1:4
	ds_read2_b64 v[122:125], v146 offset0:8 offset1:12
	ds_read2_b64 v[168:171], v146 offset0:16 offset1:20
	v_cvt_pk_bf16_f32 v110, v78, v79
	v_cvt_pk_bf16_f32 v111, v80, v81
	v_cvt_pk_bf16_f32 v112, v82, v83
	v_cvt_pk_bf16_f32 v113, v84, v85
	v_cvt_pk_bf16_f32 v114, v86, v87
	v_cvt_pk_bf16_f32 v115, v88, v89
	v_cvt_pk_bf16_f32 v116, v90, v91
	v_cvt_pk_bf16_f32 v117, v92, v93
	v_add_u32_e32 v179, s59, v214
	s_waitcnt lgkmcnt(2)
	v_mfma_f32_16x16x32_bf16 v[240:243], v[118:121], v[94:97], 0
	ds_read2_b64 v[118:121], v146 offset0:24 offset1:28
	s_waitcnt lgkmcnt(2)
	v_mfma_f32_16x16x32_bf16 v[240:243], v[122:125], v[98:101], v[240:243]
	v_add_u32_e32 v236, 0xd000, v250
	ds_read2_b64 v[122:125], v236 offset0:0 offset1:4
	s_waitcnt lgkmcnt(2)
	v_mfma_f32_16x16x32_bf16 v[240:243], v[168:171], v[102:105], v[240:243]
	ds_read2_b64 v[168:171], v236 offset0:8 offset1:12
	s_waitcnt lgkmcnt(2)
	v_mfma_f32_16x16x32_bf16 v[240:243], v[118:121], v[106:109], v[240:243]
	v_add_u32_e32 v146, 0x5500, v244
	ds_read2_b64 v[118:121], v146 offset0:0 offset1:4
	s_waitcnt lgkmcnt(2)
	v_mfma_f32_16x16x32_bf16 v[240:243], v[122:125], v[110:113], v[240:243]
	ds_read2_b64 v[122:125], v146 offset0:8 offset1:12
	s_waitcnt lgkmcnt(2)
	v_mfma_f32_16x16x32_bf16 v[240:243], v[168:171], v[114:117], v[240:243]
	ds_read2_b64 v[168:171], v146 offset0:16 offset1:20
	s_waitcnt lgkmcnt(2)
	v_mfma_f32_16x16x32_bf16 v[246:249], v[118:121], v[94:97], 0
	ds_read2_b64 v[118:121], v146 offset0:24 offset1:28
	s_waitcnt lgkmcnt(2)
	v_mfma_f32_16x16x32_bf16 v[246:249], v[122:125], v[98:101], v[246:249]
	v_add_u32_e32 v236, 0xd900, v250
	ds_read2_b64 v[122:125], v236 offset0:0 offset1:4
	s_waitcnt lgkmcnt(2)
	v_mfma_f32_16x16x32_bf16 v[246:249], v[168:171], v[102:105], v[246:249]
	ds_read2_b64 v[168:171], v236 offset0:8 offset1:12
	s_waitcnt lgkmcnt(2)
	v_mfma_f32_16x16x32_bf16 v[246:249], v[118:121], v[106:109], v[246:249]
	v_add_u32_e32 v146, 0x6600, v244
	ds_read2_b64 v[118:121], v146 offset0:0 offset1:4
	s_waitcnt lgkmcnt(2)
	v_mfma_f32_16x16x32_bf16 v[246:249], v[122:125], v[110:113], v[246:249]
	ds_read2_b64 v[122:125], v146 offset0:8 offset1:12
	s_waitcnt lgkmcnt(2)
	v_mfma_f32_16x16x32_bf16 v[246:249], v[168:171], v[114:117], v[246:249]
	ds_read2_b64 v[168:171], v146 offset0:16 offset1:20
	v_add_u32_e32 v178, 0, v179
	v_mad_u64_u32 v[176:177], s[52:53], v178, s51, v[166:167]
	v_cvt_pk_bf16_f32 v178, v240, v240
	global_store_short v[176:177], v178, off offset:0
	s_nop 0
	v_cvt_pk_bf16_f32 v178, v241, v241
	global_store_short v[176:177], v178, off offset:1024
	s_nop 0
	v_cvt_pk_bf16_f32 v178, v242, v242
	global_store_short v[176:177], v178, off offset:2048
	s_nop 0
	v_cvt_pk_bf16_f32 v178, v243, v243
	global_store_short v[176:177], v178, off offset:3072
	s_waitcnt lgkmcnt(2)
	v_mfma_f32_16x16x32_bf16 v[240:243], v[118:121], v[94:97], 0
	ds_read2_b64 v[118:121], v146 offset0:24 offset1:28
	s_waitcnt lgkmcnt(2)
	v_mfma_f32_16x16x32_bf16 v[240:243], v[122:125], v[98:101], v[240:243]
	v_add_u32_e32 v236, 0xe200, v250
	ds_read2_b64 v[122:125], v236 offset0:0 offset1:4
	s_waitcnt lgkmcnt(2)
	v_mfma_f32_16x16x32_bf16 v[240:243], v[168:171], v[102:105], v[240:243]
	ds_read2_b64 v[168:171], v236 offset0:8 offset1:12
	s_waitcnt lgkmcnt(2)
	v_mfma_f32_16x16x32_bf16 v[240:243], v[118:121], v[106:109], v[240:243]
	v_add_u32_e32 v146, 0x7700, v244
	ds_read2_b64 v[118:121], v146 offset0:0 offset1:4
	s_waitcnt lgkmcnt(2)
	v_mfma_f32_16x16x32_bf16 v[240:243], v[122:125], v[110:113], v[240:243]
	ds_read2_b64 v[122:125], v146 offset0:8 offset1:12
	s_waitcnt lgkmcnt(2)
	v_mfma_f32_16x16x32_bf16 v[240:243], v[168:171], v[114:117], v[240:243]
	ds_read2_b64 v[168:171], v146 offset0:16 offset1:20
	v_add_u32_e32 v178, 16, v179
	v_mad_u64_u32 v[176:177], s[52:53], v178, s51, v[166:167]
	v_cvt_pk_bf16_f32 v178, v246, v246
	global_store_short v[176:177], v178, off offset:0
	s_nop 0
	v_cvt_pk_bf16_f32 v178, v247, v247
	global_store_short v[176:177], v178, off offset:1024
	s_nop 0
	v_cvt_pk_bf16_f32 v178, v248, v248
	global_store_short v[176:177], v178, off offset:2048
	s_nop 0
	v_cvt_pk_bf16_f32 v178, v249, v249
	global_store_short v[176:177], v178, off offset:3072
	s_waitcnt lgkmcnt(2)
	v_mfma_f32_16x16x32_bf16 v[246:249], v[118:121], v[94:97], 0
	ds_read2_b64 v[118:121], v146 offset0:24 offset1:28
	s_waitcnt lgkmcnt(2)
	v_mfma_f32_16x16x32_bf16 v[246:249], v[122:125], v[98:101], v[246:249]
	v_add_u32_e32 v236, 0xeb00, v250
	ds_read2_b64 v[122:125], v236 offset0:0 offset1:4
	s_waitcnt lgkmcnt(2)
	v_mfma_f32_16x16x32_bf16 v[246:249], v[168:171], v[102:105], v[246:249]
	ds_read2_b64 v[168:171], v236 offset0:8 offset1:12
	s_waitcnt lgkmcnt(2)
	v_mfma_f32_16x16x32_bf16 v[246:249], v[118:121], v[106:109], v[246:249]
	s_waitcnt lgkmcnt(1)
	v_mfma_f32_16x16x32_bf16 v[246:249], v[122:125], v[110:113], v[246:249]
	s_waitcnt lgkmcnt(0)
	v_mfma_f32_16x16x32_bf16 v[246:249], v[168:171], v[114:117], v[246:249]
	v_add_u32_e32 v178, 32, v179
	v_mad_u64_u32 v[176:177], s[52:53], v178, s51, v[166:167]
	v_cvt_pk_bf16_f32 v178, v240, v240
	global_store_short v[176:177], v178, off offset:0
	s_nop 0
	v_cvt_pk_bf16_f32 v178, v241, v241
	global_store_short v[176:177], v178, off offset:1024
	s_nop 0
	v_cvt_pk_bf16_f32 v178, v242, v242
	global_store_short v[176:177], v178, off offset:2048
	s_nop 0
	v_cvt_pk_bf16_f32 v178, v243, v243
	global_store_short v[176:177], v178, off offset:3072
	v_add_u32_e32 v236, 0x8800, v250
	ds_read2_b64 v[94:97], v236 offset0:0 offset1:4
	ds_read2_b64 v[98:101], v236 offset0:8 offset1:12
	v_add_u32_e32 v236, 0x9100, v250
	ds_read2_b64 v[102:105], v236 offset0:0 offset1:4
	ds_read2_b64 v[106:109], v236 offset0:8 offset1:12
	v_add_u32_e32 v236, 0x9a00, v250
	ds_read2_b64 v[118:121], v236 offset0:0 offset1:4
	ds_read2_b64 v[122:125], v236 offset0:8 offset1:12
	v_mul_f32_e32 v2, v162, v2
	v_mul_f32_e32 v3, v162, v3
	v_mul_f32_e32 v4, v162, v4
	v_mul_f32_e32 v5, v162, v5
	v_mul_f32_e32 v6, v162, v6
	v_mul_f32_e32 v7, v162, v7
	v_mul_f32_e32 v8, v162, v8
	v_mul_f32_e32 v9, v162, v9
	v_mul_f32_e32 v10, v162, v10
	v_mul_f32_e32 v11, v162, v11
	v_mul_f32_e32 v12, v162, v12
	v_mul_f32_e32 v13, v162, v13
	v_mul_f32_e32 v14, v162, v14
	v_mul_f32_e32 v15, v162, v15
	v_mul_f32_e32 v16, v162, v16
	v_mul_f32_e32 v17, v162, v17
	v_mul_f32_e32 v18, v162, v18
	v_mul_f32_e32 v19, v162, v19
	v_mul_f32_e32 v20, v162, v20
	v_mul_f32_e32 v21, v162, v21
	v_mul_f32_e32 v22, v162, v22
	v_mul_f32_e32 v23, v162, v23
	v_mul_f32_e32 v24, v162, v24
	v_mul_f32_e32 v25, v162, v25
	v_mul_f32_e32 v42, v162, v42
	v_mul_f32_e32 v43, v162, v43
	v_mul_f32_e32 v44, v162, v44
	v_mul_f32_e32 v45, v162, v45
	v_mul_f32_e32 v46, v162, v46
	v_mul_f32_e32 v47, v162, v47
	v_mul_f32_e32 v48, v162, v48
	v_mul_f32_e32 v49, v162, v49
	v_add_u32_e32 v178, 48, v179
	v_mad_u64_u32 v[176:177], s[52:53], v178, s51, v[166:167]
	v_cvt_pk_bf16_f32 v178, v246, v246
	global_store_short v[176:177], v178, off offset:0
	s_nop 0
	v_cvt_pk_bf16_f32 v178, v247, v247
	global_store_short v[176:177], v178, off offset:1024
	s_nop 0
	v_cvt_pk_bf16_f32 v178, v248, v248
	global_store_short v[176:177], v178, off offset:2048
	s_nop 0
	v_cvt_pk_bf16_f32 v178, v249, v249
	global_store_short v[176:177], v178, off offset:3072
	v_add_u32_e32 v236, 0xa300, v250
	ds_read2_b64 v[168:171], v236 offset0:0 offset1:4
	ds_read2_b64 v[176:179], v236 offset0:8 offset1:12
	s_waitcnt lgkmcnt(7)
	v_mfma_f32_16x16x32_bf16 v[2:5], v[94:97], v[110:113], v[2:5]
	v_add_u32_e32 v236, 0xac00, v250
	ds_read2_b64 v[94:97], v236 offset0:0 offset1:4
	s_waitcnt lgkmcnt(7)
	v_mfma_f32_16x16x32_bf16 v[2:5], v[98:101], v[114:117], v[2:5]
	ds_read2_b64 v[98:101], v236 offset0:8 offset1:12
	s_waitcnt lgkmcnt(7)
	v_mfma_f32_16x16x32_bf16 v[6:9], v[102:105], v[110:113], v[6:9]
	v_add_u32_e32 v236, 0xb500, v250
	ds_read2_b64 v[102:105], v236 offset0:0 offset1:4
	s_waitcnt lgkmcnt(7)
	v_mfma_f32_16x16x32_bf16 v[6:9], v[106:109], v[114:117], v[6:9]
	ds_read2_b64 v[106:109], v236 offset0:8 offset1:12
	s_waitcnt lgkmcnt(7)
	v_mfma_f32_16x16x32_bf16 v[10:13], v[118:121], v[110:113], v[10:13]
	v_add_u32_e32 v236, 0xbe00, v250
	ds_read2_b64 v[118:121], v236 offset0:0 offset1:4
	s_waitcnt lgkmcnt(7)
	v_mfma_f32_16x16x32_bf16 v[10:13], v[122:125], v[114:117], v[10:13]
	ds_read2_b64 v[122:125], v236 offset0:8 offset1:12
	s_waitcnt lgkmcnt(7)
	v_mfma_f32_16x16x32_bf16 v[14:17], v[168:171], v[110:113], v[14:17]
	v_add_u32_e32 v236, 0xc700, v250
	ds_read2_b64 v[168:171], v236 offset0:0 offset1:4
	s_waitcnt lgkmcnt(7)
	v_mfma_f32_16x16x32_bf16 v[14:17], v[176:179], v[114:117], v[14:17]
	ds_read2_b64 v[176:179], v236 offset0:8 offset1:12
	s_waitcnt lgkmcnt(7)
	v_mfma_f32_16x16x32_bf16 v[18:21], v[94:97], v[110:113], v[18:21]
	s_waitcnt lgkmcnt(6)
	v_mfma_f32_16x16x32_bf16 v[18:21], v[98:101], v[114:117], v[18:21]
	s_waitcnt lgkmcnt(5)
	v_mfma_f32_16x16x32_bf16 v[22:25], v[102:105], v[110:113], v[22:25]
	s_waitcnt lgkmcnt(4)
	v_mfma_f32_16x16x32_bf16 v[22:25], v[106:109], v[114:117], v[22:25]
	s_waitcnt lgkmcnt(3)
	v_mfma_f32_16x16x32_bf16 v[42:45], v[118:121], v[110:113], v[42:45]
	s_waitcnt lgkmcnt(2)
	v_mfma_f32_16x16x32_bf16 v[42:45], v[122:125], v[114:117], v[42:45]
	s_waitcnt lgkmcnt(1)
	v_mfma_f32_16x16x32_bf16 v[46:49], v[168:171], v[110:113], v[46:49]
	s_waitcnt lgkmcnt(0)
	v_mfma_f32_16x16x32_bf16 v[46:49], v[176:179], v[114:117], v[46:49]
	s_waitcnt vmcnt(4)
	v_mov_b32_e32 v162, v239
	v_lshlrev_b32_e32 v78, 16, v26
	v_lshlrev_b32_e32 v79, 16, v27
	v_lshlrev_b32_e32 v80, 16, v28
	v_lshlrev_b32_e32 v81, 16, v29
	v_lshlrev_b32_e32 v82, 16, v30
	v_lshlrev_b32_e32 v83, 16, v31
	v_lshlrev_b32_e32 v84, 16, v32
	v_lshlrev_b32_e32 v85, 16, v33
	v_lshlrev_b32_e32 v86, 16, v34
	v_lshlrev_b32_e32 v87, 16, v35
	v_lshlrev_b32_e32 v88, 16, v36
	v_lshlrev_b32_e32 v89, 16, v37
	v_lshlrev_b32_e32 v90, 16, v38
	v_lshlrev_b32_e32 v91, 16, v39
	v_lshlrev_b32_e32 v92, 16, v40
	v_lshlrev_b32_e32 v93, 16, v41
	s_nop 4
	s_branch .LBB0_308
